# static s_setprio 1 for waves 4-7 on all six compiled GEMM K-loops (phases 1,3,7,10,12,13); flips deleted
# baseline (speedup 1.0000x reference)
;     __device__ __forceinline__ bool next(int i, Unit& u) const { if (i != 0 || c >= n) return false; u.pm = 0; u.pn = c; u.kt0 = 0; u.nkt = ntk; u.piece = -1; return true; }
; #define PG8_STAGE(bufoff, gbase, voff) do { _Pragma("unroll") for (int _i = 0; _i < 2; ++_i) \
;         __builtin_amdgcn_global_load_lds((const unsigned*)((const char*)(gbase) + (voff)[_i]), (LAS unsigned*)(lds + (bufoff) + ldsw + _i * 8192), 16, 0, 0); } while (0)
; #define PG8_WAIT_V(n) asm volatile("s_waitcnt vmcnt(" #n ")" ::: "memory")
; #define PG8_BAR __builtin_amdgcn_s_barrier()
; template <class Epi, class Sched>
; __device__ __forceinline__ void gemm_phase(LAS unsigned char* lds, const Gemm g, const Sched& S, const Epi& E) {
;     ...
;     Unit cur, nxt; int ui = 0;
;     if (!S.next(0, cur)) return;
;     f32x4 acc[2][2][4][2];
; #pragma unroll
;     for (int a = 0; a < 2; ++a)
; #pragma unroll
;         for (int b = 0; b < 2; ++b)
; #pragma unroll
;             for (int m = 0; m < 4; ++m)
; #pragma unroll
;                 for (int n = 0; n < 2; ++n) acc[a][b][m][n] = (f32x4){0.f, 0.f, 0.f, 0.f};
;     bf16x8 At[4][2], B0[2][2], B1[2][2];
;     const char* cA = (const char*)g.A + (size_t)cur.pm * tstepA + (size_t)cur.pn * g.a_pn_off + (size_t)cur.kt0 * kstep; const char* cB = (const char*)g.Bt + (size_t)cur.pn * tstepB + (size_t)cur.kt0 * kstep;
;     PG8_STAGE(PG8_SB(0, 0), cB, voffB); PG8_STAGE(PG8_SA(0, 0), cA, voffA); PG8_STAGE(PG8_SB(0, 1), cB + hstepB, voffB); PG8_STAGE(PG8_SA(0, 1), cA + hstepA, voffA);
;     if (wr == 1) PG8_BAR;
;     PG8_WAIT_V(4); PG8_BAR;
;     PG8_STAGE(PG8_SB(1, 0), cB + kstep, voffB); PG8_STAGE(PG8_SA(1, 0), cA + kstep, voffA); PG8_STAGE(PG8_SB(1, 1), cB + hstepB + kstep, voffB);
;     PG8_WAIT_V(6); PG8_BAR;
.LBB0_298:
	v_and_b32_e32 v90, 3, v166
	s_lshl_b32 s12, s12, 5
	v_lshlrev_b32_e32 v8, 4, v90
	v_lshlrev_b32_e32 v9, 6, v160
	s_movk_i32 s13, 0x3c0
	s_and_b32 s24, s12, 0x60
	v_and_or_b32 v9, v9, s13, v8
	s_lshl_b32 s13, s16, 13
	s_lshl_b32 s12, s24, 7
	v_and_b32_e32 v88, 15, v160
	s_add_u32 s14, s84, 0x7780080
	v_and_b32_e32 v10, 32, v184
	v_lshl_or_b32 v8, v88, 6, v8
	s_addc_u32 s15, s85, 0
	v_bitop3_b32 v16, v8, s13, v10 bitop3:0xde
	v_bitop3_b32 v17, s12, v9, v10 bitop3:0xf6
	s_mov_b64 s[12:13], 0x80
	v_lshl_add_u64 v[8:9], s[14:15], 0, v[82:83]
	v_lshl_add_u64 v[10:11], s[14:15], 0, v[80:81]
	s_add_u32 s14, s10, 0x80080
	v_lshl_add_u64 v[0:1], v[0:1], 0, s[12:13]
	s_addc_u32 s15, s11, 0
	s_add_i32 m0, s20, 0x18000
	v_lshl_add_u64 v[2:3], v[2:3], 0, s[12:13]
	s_waitcnt vmcnt(4)
	s_barrier
	global_load_lds_dwordx4 v[0:1], off
	s_add_i32 m0, s20, 0x1a000
	s_add_i32 s25, s20, 0x8000
	global_load_lds_dwordx4 v[2:3], off
	s_mov_b32 m0, s25
	s_add_i32 s26, s20, 0xa000
	global_load_lds_dwordx4 v[8:9], off
	s_mov_b32 m0, s26
	v_lshl_add_u64 v[12:13], s[14:15], 0, v[82:83]
	global_load_lds_dwordx4 v[10:11], off
	s_add_i32 m0, s20, 0x1c000
	v_lshl_add_u64 v[14:15], s[14:15], 0, v[80:81]
	global_load_lds_dwordx4 v[12:13], off
	s_add_i32 m0, s20, 0x1e000
	v_lshlrev_b32_e32 v0, 9, v160
	global_load_lds_dwordx4 v[14:15], off
	v_and_b32_e32 v0, 0x70000, v0
	v_lshlrev_b32_e32 v2, 12, v7
	v_or3_b32 v0, v5, v0, v2
	v_add_u32_e32 v0, v0, v6
	v_mov_b32_e32 v1, v83
	s_load_dwordx2 s[6:7], s[0:1], 0x40
	v_lshl_add_u64 v[84:85], s[84:85], 0, v[0:1]
	v_lshlrev_b32_e32 v0, 5, v4
	v_and_b32_e32 v0, 0xf0000, v0
	s_waitcnt vmcnt(6)
	v_or3_b32 v0, v5, v0, v2
	s_add_i32 s30, 0, 0x10000
	s_add_i32 s34, 0, 0x14000
	s_add_i32 s36, 0, 0x18000
	s_add_i32 s38, 0, 0x1c000
	v_add_u32_e32 v0, v0, v6
	v_add_u32_e32 v91, s30, v17
	v_add_u32_e32 v93, s34, v17
	s_add_i32 s30, s30, s17
	s_add_i32 s34, s34, s17
	v_add_u32_e32 v94, s36, v17
	v_add_u32_e32 v95, s38, v17
	s_add_i32 s36, s36, s17
	s_add_i32 s38, s38, s17
	v_lshl_add_u64 v[86:87], s[84:85], 0, v[0:1]
	s_mov_b32 s27, -2
	s_mov_b64 s[14:15], 0x7800080
	v_add_u32_e32 v92, 0, v16
	s_add_i32 s28, s20, 0xc000
	s_add_i32 s29, s20, 0xe000
	s_add_i32 s31, s30, 0x2000
	s_add_i32 s35, s34, 0x2000
	s_add_i32 s37, s36, 0x2000
	s_add_i32 s39, s38, 0x2000
	v_mov_b32_e32 v0, v83
	v_mov_b32_e32 v2, v83
	v_mov_b32_e32 v3, v83
	v_mov_b32_e32 v4, v83
	v_mov_b32_e32 v5, v83
	v_mov_b32_e32 v6, v83
	v_mov_b32_e32 v7, v83
	v_mov_b32_e32 v8, v83
	v_mov_b32_e32 v9, v83
	v_mov_b32_e32 v10, v83
	v_mov_b32_e32 v11, v83
	v_mov_b32_e32 v12, v83
	v_mov_b32_e32 v13, v83
	v_mov_b32_e32 v14, v83
	v_mov_b32_e32 v15, v83
	v_mov_b32_e32 v16, v83
	v_mov_b32_e32 v17, v83
	v_mov_b32_e32 v18, v83
	v_mov_b32_e32 v19, v83
	v_mov_b32_e32 v20, v83
	v_mov_b32_e32 v21, v83
	v_mov_b32_e32 v22, v83
	v_mov_b32_e32 v23, v83
	v_mov_b32_e32 v32, v83
	v_mov_b32_e32 v33, v83
	v_mov_b32_e32 v34, v83
	v_mov_b32_e32 v35, v83
	v_mov_b32_e32 v36, v83
	v_mov_b32_e32 v37, v83
	v_mov_b32_e32 v38, v83
	v_mov_b32_e32 v39, v83
	v_mov_b32_e32 v48, v83
	v_mov_b32_e32 v49, v83
	v_mov_b32_e32 v50, v83
	v_mov_b32_e32 v51, v83
	v_mov_b32_e32 v52, v83
	v_mov_b32_e32 v53, v83
	v_mov_b32_e32 v54, v83
	v_mov_b32_e32 v55, v83
	v_mov_b32_e32 v64, v83
	v_mov_b32_e32 v65, v83
	v_mov_b32_e32 v66, v83
	v_mov_b32_e32 v67, v83
	v_mov_b32_e32 v68, v83
	v_mov_b32_e32 v69, v83
	v_mov_b32_e32 v70, v83
	v_mov_b32_e32 v71, v83
	v_mov_b32_e32 v24, v83
	v_mov_b32_e32 v25, v83
	v_mov_b32_e32 v26, v83
	v_mov_b32_e32 v27, v83
	v_mov_b32_e32 v28, v83
	v_mov_b32_e32 v29, v83
	v_mov_b32_e32 v30, v83
	v_mov_b32_e32 v31, v83
	v_mov_b32_e32 v40, v83
	v_mov_b32_e32 v41, v83
	v_mov_b32_e32 v42, v83
	v_mov_b32_e32 v43, v83
	v_mov_b32_e32 v44, v83
	v_mov_b32_e32 v45, v83
	v_mov_b32_e32 v46, v83
	v_mov_b32_e32 v47, v83
	v_mov_b32_e32 v56, v83
	v_mov_b32_e32 v57, v83
	v_mov_b32_e32 v58, v83
	v_mov_b32_e32 v59, v83
	v_mov_b32_e32 v60, v83
	v_mov_b32_e32 v61, v83
	v_mov_b32_e32 v62, v83
	v_mov_b32_e32 v63, v83
	v_mov_b32_e32 v72, v83
	v_mov_b32_e32 v73, v83
	v_mov_b32_e32 v74, v83
	v_mov_b32_e32 v75, v83
	v_mov_b32_e32 v76, v83
	v_mov_b32_e32 v77, v83
	v_mov_b32_e32 v78, v83
	v_mov_b32_e32 v79, v83
	v_lshl_or_b32 v89, s16, 6, v88
	s_barrier
	s_lshr_b32 s48, s3, 8
	s_cmp_lg_u32 s48, 0
	s_cbranch_scc0 .Lprio_299
	s_setprio 1
;     __device__ __forceinline__ bool next(int i, Unit& u) const { if (i != 0 || c >= n) return false; u.pm = 0; u.pn = c; u.kt0 = 0; u.nkt = ntk; u.piece = -1; return true; }
; #define PG8_STAGE(bufoff, gbase, voff) do { _Pragma("unroll") for (int _i = 0; _i < 2; ++_i) \
;         __builtin_amdgcn_global_load_lds((const unsigned*)((const char*)(gbase) + (voff)[_i]), (LAS unsigned*)(lds + (bufoff) + ldsw + _i * 8192), 16, 0, 0); } while (0)
; #define PG8_LDA(dst, b, h) do { _Pragma("unroll") for (int m = 0; m < 4; ++m) _Pragma("unroll") for (int k = 0; k < 2; ++k) dst[m][k] = *(const LAS bf16x8*)(lds + PG8_SA(b, h) + aoff + m * 2048 + k * 1024); } while (0)
; #define PG8_WAIT_V(n) asm volatile("s_waitcnt vmcnt(" #n ")" ::: "memory")
; #define PG8_WAIT_L(n) asm volatile("s_waitcnt lgkmcnt(" #n ")" ::: "memory")
; template <class Epi, class Sched>
; __device__ __forceinline__ void gemm_phase(LAS unsigned char* lds, const Gemm g, const Sched& S, const Epi& E) {
;     ...
;     for (;;) {
;         const bool has_next = S.next(ui + 1, nxt);
;         const char* nA = has_next ? (const char*)g.A + (size_t)nxt.pm * tstepA + (size_t)nxt.pn * g.a_pn_off + (size_t)nxt.kt0 * kstep : cA; const char* nB = has_next ? (const char*)g.Bt + (size_t)nxt.pn * tstepB + (size_t)nxt.kt0 * kstep : cB;
;         const int nt = cur.nkt;
; #pragma unroll 1
;         for (int t = 0; t < nt; t += 2) {
;             const bool last = (t == nt - 2);
;             const char* a1 = cA + (size_t)(t + 1) * kstep;
;             const char* a2 = last ? nA : cA + (size_t)(t + 2) * kstep; const char* b2 = last ? nB : cB + (size_t)(t + 2) * kstep;
;             const char* a3 = a2 + kstep; const char* b3 = b2 + kstep;
;             PG8_LDB(B0, 0, 0); PG8_SCHED; PG8_LDA(At, 0, 0); PG8_STAGE(PG8_SA(1, 1), a1 + hstepA, voffA);
;             PG8_WAIT_L(8); PG8_BAR; PG8_WAIT_L(0); PG8_MMA(0, 0, At, B0); PG8_BAR; PG8_SCHED;
;             PG8_LDB(B1, 0, 1); PG8_STAGE(PG8_SB(0, 0), b2, voffB);
;             PG8_BAR; PG8_WAIT_L(0); if constexpr (!Epi::DIAG) PG8_MMA(0, 1, At, B1); PG8_BAR;
;             PG8_LDA(At, 0, 1); PG8_STAGE(PG8_SA(0, 0), a2, voffA);
;             PG8_BAR; PG8_WAIT_L(0); if constexpr (!Epi::DIAG) PG8_MMA(1, 0, At, B0); PG8_BAR; PG8_SCHED;
;             PG8_STAGE(PG8_SB(0, 1), b2 + hstepB, voffB);
;             PG8_WAIT_V(6); PG8_BAR; PG8_MMA(1, 1, At, B1); PG8_BAR;
.Lprio_299:
.LBB0_299:
	s_add_u32 s16, s14, 0xf8800080
	ds_read_b128 v[96:99], v91
	ds_read_b128 v[100:103], v91 offset:1024
	ds_read_b128 v[104:107], v91 offset:2048
	ds_read_b128 v[108:111], v91 offset:3072
	s_addc_u32 s17, s15, -1
	s_cmp_lg_u32 s27, 28
	s_cselect_b32 s16, s16, 0
	s_cselect_b32 s17, s17, 0
	s_add_u32 s18, s8, s16
	s_addc_u32 s19, s9, s17
	s_add_u32 s16, s10, s16
	s_addc_u32 s17, s11, s17
	s_mov_b32 m0, s28
	v_lshl_add_u64 v[144:145], v[84:85], 0, s[14:15]
	ds_read_b128 v[112:115], v92
	ds_read_b128 v[116:119], v92 offset:1024
	ds_read_b128 v[120:123], v92 offset:2048
	ds_read_b128 v[124:127], v92 offset:3072
	ds_read_b128 v[128:131], v92 offset:4096
	ds_read_b128 v[132:135], v92 offset:5120
	ds_read_b128 v[136:139], v92 offset:6144
	ds_read_b128 v[140:143], v92 offset:7168
	global_load_lds_dwordx4 v[144:145], off
	v_lshl_add_u64 v[144:145], v[86:87], 0, s[14:15]
	s_mov_b32 m0, s29
	s_nop 0
	global_load_lds_dwordx4 v[144:145], off
	s_waitcnt lgkmcnt(8)
	s_barrier
	s_waitcnt lgkmcnt(0)
	s_waitcnt lgkmcnt(0)
	v_mfma_f32_16x16x32_bf16 v[76:79], v[96:99], v[112:115], v[76:79]
	v_mfma_f32_16x16x32_bf16 v[72:75], v[104:107], v[112:115], v[72:75]
	v_mfma_f32_16x16x32_bf16 v[60:63], v[96:99], v[120:123], v[60:63]
	v_mfma_f32_16x16x32_bf16 v[56:59], v[104:107], v[120:123], v[56:59]
	v_mfma_f32_16x16x32_bf16 v[44:47], v[96:99], v[128:131], v[44:47]
	v_mfma_f32_16x16x32_bf16 v[40:43], v[104:107], v[128:131], v[40:43]
	v_mfma_f32_16x16x32_bf16 v[28:31], v[96:99], v[136:139], v[28:31]
	v_mfma_f32_16x16x32_bf16 v[24:27], v[104:107], v[136:139], v[24:27]
	v_mfma_f32_16x16x32_bf16 v[76:79], v[100:103], v[116:119], v[76:79]
	v_mfma_f32_16x16x32_bf16 v[72:75], v[108:111], v[116:119], v[72:75]
	v_mfma_f32_16x16x32_bf16 v[60:63], v[100:103], v[124:127], v[60:63]
	v_mfma_f32_16x16x32_bf16 v[56:59], v[108:111], v[124:127], v[56:59]
	v_mfma_f32_16x16x32_bf16 v[44:47], v[100:103], v[132:135], v[44:47]
	v_mfma_f32_16x16x32_bf16 v[40:43], v[108:111], v[132:135], v[40:43]
	v_mfma_f32_16x16x32_bf16 v[28:31], v[100:103], v[140:143], v[28:31]
	v_mfma_f32_16x16x32_bf16 v[24:27], v[108:111], v[140:143], v[24:27]
	s_barrier
	s_mov_b32 m0, s30
	v_lshl_add_u64 v[162:163], s[16:17], 0, v[82:83]
	ds_read_b128 v[144:147], v93
	ds_read_b128 v[148:151], v93 offset:1024
	ds_read_b128 v[152:155], v93 offset:2048
	ds_read_b128 v[156:159], v93 offset:3072
	global_load_lds_dwordx4 v[162:163], off
	v_lshl_add_u64 v[164:165], s[16:17], 0, v[80:81]
	s_mov_b32 m0, s31
	s_nop 0
	global_load_lds_dwordx4 v[164:165], off
	s_barrier
	s_waitcnt lgkmcnt(0)
	s_waitcnt lgkmcnt(0)
	v_mfma_f32_16x16x32_bf16 v[68:71], v[144:147], v[112:115], v[68:71]
	v_mfma_f32_16x16x32_bf16 v[64:67], v[152:155], v[112:115], v[64:67]
	v_mfma_f32_16x16x32_bf16 v[52:55], v[144:147], v[120:123], v[52:55]
	v_mfma_f32_16x16x32_bf16 v[48:51], v[152:155], v[120:123], v[48:51]
	v_mfma_f32_16x16x32_bf16 v[36:39], v[144:147], v[128:131], v[36:39]
	v_mfma_f32_16x16x32_bf16 v[32:35], v[152:155], v[128:131], v[32:35]
	v_mfma_f32_16x16x32_bf16 v[20:23], v[144:147], v[136:139], v[20:23]
	v_mfma_f32_16x16x32_bf16 v[16:19], v[152:155], v[136:139], v[16:19]
	v_mfma_f32_16x16x32_bf16 v[68:71], v[148:151], v[116:119], v[68:71]
	v_mfma_f32_16x16x32_bf16 v[64:67], v[156:159], v[116:119], v[64:67]
	v_mfma_f32_16x16x32_bf16 v[52:55], v[148:151], v[124:127], v[52:55]
	v_mfma_f32_16x16x32_bf16 v[48:51], v[156:159], v[124:127], v[48:51]
	v_mfma_f32_16x16x32_bf16 v[36:39], v[148:151], v[132:135], v[36:39]
	v_mfma_f32_16x16x32_bf16 v[32:35], v[156:159], v[132:135], v[32:35]
	v_mfma_f32_16x16x32_bf16 v[20:23], v[148:151], v[140:143], v[20:23]
	v_mfma_f32_16x16x32_bf16 v[16:19], v[156:159], v[140:143], v[16:19]
	s_mov_b32 m0, s20
	v_lshl_add_u64 v[168:169], s[18:19], 0, v[82:83]
	s_barrier
	ds_read_b128 v[112:115], v92 offset:16384
	ds_read_b128 v[116:119], v92 offset:17408
	global_load_lds_dwordx4 v[168:169], off
	v_lshl_add_u64 v[170:171], s[18:19], 0, v[80:81]
	s_mov_b32 m0, s21
	s_nop 0
	global_load_lds_dwordx4 v[170:171], off
	s_barrier
	s_waitcnt lgkmcnt(0)
	s_waitcnt lgkmcnt(0)
	v_mfma_f32_16x16x32_bf16 v[12:15], v[96:99], v[112:115], v[12:15]
	v_mfma_f32_16x16x32_bf16 v[8:11], v[104:107], v[112:115], v[8:11]
	v_mfma_f32_16x16x32_bf16 v[12:15], v[100:103], v[116:119], v[12:15]
	v_mfma_f32_16x16x32_bf16 v[8:11], v[108:111], v[116:119], v[8:11]
	s_barrier
	s_add_u32 s40, s16, 0x80000
	s_addc_u32 s41, s17, 0
	s_mov_b32 m0, s34
	v_lshl_add_u64 v[96:97], s[40:41], 0, v[82:83]
	global_load_lds_dwordx4 v[96:97], off
	v_lshl_add_u64 v[96:97], s[40:41], 0, v[80:81]
	s_mov_b32 m0, s35
	s_nop 0
	global_load_lds_dwordx4 v[96:97], off
	s_waitcnt vmcnt(6)
	s_barrier
	v_mfma_f32_16x16x32_bf16 v[4:7], v[144:147], v[112:115], v[4:7]
	v_mfma_f32_16x16x32_bf16 v[0:3], v[152:155], v[112:115], v[0:3]
	v_mfma_f32_16x16x32_bf16 v[4:7], v[148:151], v[116:119], v[4:7]
	v_mfma_f32_16x16x32_bf16 v[0:3], v[156:159], v[116:119], v[0:3]
	s_barrier
	ds_read_b128 v[96:99], v94
	ds_read_b128 v[100:103], v94 offset:1024
	ds_read_b128 v[104:107], v94 offset:2048
	ds_read_b128 v[108:111], v94 offset:3072
	s_add_u32 s18, s18, 0x80000
	s_addc_u32 s19, s19, 0
	s_mov_b32 m0, s22
	v_lshl_add_u64 v[144:145], s[18:19], 0, v[82:83]
	ds_read_b128 v[112:115], v92 offset:32768
	ds_read_b128 v[116:119], v92 offset:33792
	ds_read_b128 v[120:123], v92 offset:34816
	ds_read_b128 v[124:127], v92 offset:35840
	ds_read_b128 v[128:131], v92 offset:36864
	ds_read_b128 v[132:135], v92 offset:37888
	ds_read_b128 v[136:139], v92 offset:38912
	ds_read_b128 v[140:143], v92 offset:39936
	global_load_lds_dwordx4 v[144:145], off
	v_lshl_add_u64 v[144:145], s[18:19], 0, v[80:81]
	s_mov_b32 m0, s23
	s_nop 0
	global_load_lds_dwordx4 v[144:145], off
	s_waitcnt lgkmcnt(8)
	s_barrier
; #define PG8_STAGE(bufoff, gbase, voff) do { _Pragma("unroll") for (int _i = 0; _i < 2; ++_i) \
;         __builtin_amdgcn_global_load_lds((const unsigned*)((const char*)(gbase) + (voff)[_i]), (LAS unsigned*)(lds + (bufoff) + ldsw + _i * 8192), 16, 0, 0); } while (0)
; #define PG8_LDA(dst, b, h) do { _Pragma("unroll") for (int m = 0; m < 4; ++m) _Pragma("unroll") for (int k = 0; k < 2; ++k) dst[m][k] = *(const LAS bf16x8*)(lds + PG8_SA(b, h) + aoff + m * 2048 + k * 1024); } while (0)
; #define PG8_LDB(dst, b, h) do { _Pragma("unroll") for (int n = 0; n < 2; ++n) _Pragma("unroll") for (int k = 0; k < 2; ++k) dst[n][k] = *(const LAS bf16x8*)(lds + PG8_SB(b, h) + boff + n * 2048 + k * 1024); } while (0)
; #define PG8_WAIT_V(n) asm volatile("s_waitcnt vmcnt(" #n ")" ::: "memory")
; #define PG8_BAR __builtin_amdgcn_s_barrier()
; template <class Epi, class Sched>
; __device__ __forceinline__ void gemm_phase(LAS unsigned char* lds, const Gemm g, const Sched& S, const Epi& E) {
;     ...
;             PG8_LDB(B0, 1, 0); PG8_SCHED; PG8_LDA(At, 1, 0); PG8_STAGE(PG8_SA(0, 1), a2 + hstepA, voffA);
;             PG8_WAIT_L(8); PG8_BAR; PG8_WAIT_L(0); PG8_MMA(0, 0, At, B0); PG8_BAR; PG8_SCHED;
;             PG8_LDB(B1, 1, 1); PG8_STAGE(PG8_SB(1, 0), b3, voffB);
;             PG8_BAR; PG8_WAIT_L(0); if constexpr (!Epi::DIAG) PG8_MMA(0, 1, At, B1); PG8_BAR;
;             PG8_LDA(At, 1, 1); PG8_STAGE(PG8_SA(1, 0), a3, voffA);
;             PG8_BAR; PG8_WAIT_L(0); if constexpr (!Epi::DIAG) PG8_MMA(1, 0, At, B0); PG8_BAR; PG8_SCHED;
;             PG8_STAGE(PG8_SB(1, 1), b3 + hstepB, voffB);
;             PG8_WAIT_V(6); PG8_BAR; PG8_MMA(1, 1, At, B1); PG8_BAR;
;         }
;         E(acc, cur, wr, wc, fr, fq);
;         if (!has_next) break;
;     __device__ __forceinline__ void operator()(const Acc& acc, const Unit& u, int wr, int wc, int fr, int fq) const {
;         const int row0 = wr * 64 + fr, col0 = u.pn * BM + wc * 32 + 4 * fq;
; #pragma unroll
;         for (int ai = 0; ai < 2; ++ai)
; #pragma unroll
;             for (int m = 0; m < 4; ++m) { const int row = row0 + ai * HALF + m * 16; if (row < NB) {
; #pragma unroll
;                 for (int bj = 0; bj < 2; ++bj)
; #pragma unroll
;                     for (int n = 0; n < 2; ++n) { const int c = col0 + bj * HALF + n * 16; *(f32x4*)(C + (size_t)row * MODW + c) = acc[ai][bj][m][n] + *(const f32x4*)(bias + c); } } }
	s_waitcnt lgkmcnt(0)
	s_waitcnt lgkmcnt(0)
	v_mfma_f32_16x16x32_bf16 v[76:79], v[96:99], v[112:115], v[76:79]
	v_mfma_f32_16x16x32_bf16 v[72:75], v[104:107], v[112:115], v[72:75]
	v_mfma_f32_16x16x32_bf16 v[60:63], v[96:99], v[120:123], v[60:63]
	v_mfma_f32_16x16x32_bf16 v[56:59], v[104:107], v[120:123], v[56:59]
	v_mfma_f32_16x16x32_bf16 v[44:47], v[96:99], v[128:131], v[44:47]
	v_mfma_f32_16x16x32_bf16 v[40:43], v[104:107], v[128:131], v[40:43]
	v_mfma_f32_16x16x32_bf16 v[28:31], v[96:99], v[136:139], v[28:31]
	v_mfma_f32_16x16x32_bf16 v[24:27], v[104:107], v[136:139], v[24:27]
	v_mfma_f32_16x16x32_bf16 v[76:79], v[100:103], v[116:119], v[76:79]
	v_mfma_f32_16x16x32_bf16 v[72:75], v[108:111], v[116:119], v[72:75]
	v_mfma_f32_16x16x32_bf16 v[60:63], v[100:103], v[124:127], v[60:63]
	v_mfma_f32_16x16x32_bf16 v[56:59], v[108:111], v[124:127], v[56:59]
	v_mfma_f32_16x16x32_bf16 v[44:47], v[100:103], v[132:135], v[44:47]
	v_mfma_f32_16x16x32_bf16 v[40:43], v[108:111], v[132:135], v[40:43]
	v_mfma_f32_16x16x32_bf16 v[28:31], v[100:103], v[140:143], v[28:31]
	v_mfma_f32_16x16x32_bf16 v[24:27], v[108:111], v[140:143], v[24:27]
	s_barrier
	s_mov_b32 m0, s36
	v_lshl_add_u64 v[162:163], v[162:163], 0, s[12:13]
	ds_read_b128 v[144:147], v95
	ds_read_b128 v[148:151], v95 offset:1024
	ds_read_b128 v[152:155], v95 offset:2048
	ds_read_b128 v[156:159], v95 offset:3072
	global_load_lds_dwordx4 v[162:163], off
	v_lshl_add_u64 v[162:163], v[164:165], 0, s[12:13]
	s_mov_b32 m0, s37
	s_nop 0
	global_load_lds_dwordx4 v[162:163], off
	s_barrier
	s_waitcnt lgkmcnt(0)
	s_waitcnt lgkmcnt(0)
	v_mfma_f32_16x16x32_bf16 v[68:71], v[144:147], v[112:115], v[68:71]
	v_mfma_f32_16x16x32_bf16 v[64:67], v[152:155], v[112:115], v[64:67]
	v_mfma_f32_16x16x32_bf16 v[52:55], v[144:147], v[120:123], v[52:55]
	v_mfma_f32_16x16x32_bf16 v[48:51], v[152:155], v[120:123], v[48:51]
	v_mfma_f32_16x16x32_bf16 v[36:39], v[144:147], v[128:131], v[36:39]
	v_mfma_f32_16x16x32_bf16 v[32:35], v[152:155], v[128:131], v[32:35]
	v_mfma_f32_16x16x32_bf16 v[20:23], v[144:147], v[136:139], v[20:23]
	v_mfma_f32_16x16x32_bf16 v[16:19], v[152:155], v[136:139], v[16:19]
	v_mfma_f32_16x16x32_bf16 v[68:71], v[148:151], v[116:119], v[68:71]
	v_mfma_f32_16x16x32_bf16 v[64:67], v[156:159], v[116:119], v[64:67]
	v_mfma_f32_16x16x32_bf16 v[52:55], v[148:151], v[124:127], v[52:55]
	v_mfma_f32_16x16x32_bf16 v[48:51], v[156:159], v[124:127], v[48:51]
	v_mfma_f32_16x16x32_bf16 v[36:39], v[148:151], v[132:135], v[36:39]
	v_mfma_f32_16x16x32_bf16 v[32:35], v[156:159], v[132:135], v[32:35]
	v_mfma_f32_16x16x32_bf16 v[20:23], v[148:151], v[140:143], v[20:23]
	v_mfma_f32_16x16x32_bf16 v[16:19], v[156:159], v[140:143], v[16:19]
	s_mov_b32 m0, s25
	v_lshl_add_u64 v[120:121], v[168:169], 0, s[12:13]
	s_barrier
	ds_read_b128 v[112:115], v92 offset:49152
	ds_read_b128 v[116:119], v92 offset:50176
	global_load_lds_dwordx4 v[120:121], off
	v_lshl_add_u64 v[120:121], v[170:171], 0, s[12:13]
	s_mov_b32 m0, s26
	s_nop 0
	global_load_lds_dwordx4 v[120:121], off
	s_barrier
	s_waitcnt lgkmcnt(0)
	s_waitcnt lgkmcnt(0)
	v_mfma_f32_16x16x32_bf16 v[12:15], v[96:99], v[112:115], v[12:15]
	v_mfma_f32_16x16x32_bf16 v[8:11], v[104:107], v[112:115], v[8:11]
	v_mfma_f32_16x16x32_bf16 v[12:15], v[100:103], v[116:119], v[12:15]
	v_mfma_f32_16x16x32_bf16 v[8:11], v[108:111], v[116:119], v[8:11]
	s_barrier
	s_add_u32 s16, s16, 0x80080
	s_addc_u32 s17, s17, 0
	s_mov_b32 m0, s38
	v_lshl_add_u64 v[96:97], s[16:17], 0, v[82:83]
	global_load_lds_dwordx4 v[96:97], off
	v_lshl_add_u64 v[96:97], s[16:17], 0, v[80:81]
	s_mov_b32 m0, s39
	s_nop 0
	global_load_lds_dwordx4 v[96:97], off
	s_waitcnt vmcnt(6)
	s_barrier
	v_mfma_f32_16x16x32_bf16 v[4:7], v[144:147], v[112:115], v[4:7]
	v_mfma_f32_16x16x32_bf16 v[0:3], v[152:155], v[112:115], v[0:3]
	v_mfma_f32_16x16x32_bf16 v[4:7], v[148:151], v[116:119], v[4:7]
	v_mfma_f32_16x16x32_bf16 v[0:3], v[156:159], v[116:119], v[0:3]
	s_add_i32 s27, s27, 2
	s_add_u32 s14, s14, 0x100
	s_addc_u32 s15, s15, 0
	s_cmp_gt_u32 s27, 29
	s_barrier
	s_cbranch_scc0 .LBB0_299
	s_setprio 0
	s_add_u32 s8, s84, 0x7880000
	s_mov_b32 s10, 0xc000
	s_addc_u32 s9, s85, 0
	v_mul_lo_u32 v82, v89, s10
	s_lshl_b32 s10, s2, 8
	v_lshl_or_b32 v80, v90, 2, s10
	s_movk_i32 s12, 0x84
	v_or_b32_e32 v80, s24, v80
	v_cmp_gt_u32_e32 vcc, s12, v89
	v_ashrrev_i32_e32 v81, 31, v80
	v_lshlrev_b64 v[96:97], 2, v[80:81]
	v_lshl_add_u64 v[96:97], s[6:7], 0, v[96:97]
	global_load_dwordx4 v[100:103], v[96:97], off
	global_load_dwordx4 v[104:107], v[96:97], off offset:64
	global_load_dwordx4 v[108:111], v[96:97], off offset:512
	global_load_dwordx4 v[112:115], v[96:97], off offset:576
	s_and_saveexec_b64 s[10:11], vcc
	s_cbranch_execz .LBB0_302
	v_lshlrev_b64 v[90:91], 2, v[80:81]
	v_lshl_add_u64 v[92:93], s[6:7], 0, v[90:91]
	s_waitcnt vmcnt(0)
	s_nop 1
	v_mov_b32_e32 v84, v100
	v_mov_b32_e32 v85, v101
	v_mov_b32_e32 v86, v102
	v_mov_b32_e32 v87, v103
	v_mov_b32_e32 v83, 0
	v_lshl_add_u64 v[94:95], s[8:9], 0, v[82:83]
	v_lshl_add_u64 v[90:91], v[94:95], 0, v[90:91]
	v_pk_add_f32 v[78:79], v[78:79], v[86:87]
	v_pk_add_f32 v[76:77], v[76:77], v[84:85]
	global_store_dwordx4 v[90:91], v[76:79], off
	s_nop 1
	v_mov_b32_e32 v76, v104
	v_mov_b32_e32 v77, v105
	v_mov_b32_e32 v78, v106
	v_mov_b32_e32 v79, v107
	v_pk_add_f32 v[74:75], v[74:75], v[78:79]
	v_pk_add_f32 v[72:73], v[72:73], v[76:77]
	global_store_dwordx4 v[90:91], v[72:75], off offset:64
	s_nop 1
	v_mov_b32_e32 v72, v108
	v_mov_b32_e32 v73, v109
	v_mov_b32_e32 v74, v110
	v_mov_b32_e32 v75, v111
	v_pk_add_f32 v[70:71], v[70:71], v[74:75]
	v_pk_add_f32 v[68:69], v[68:69], v[72:73]
	global_store_dwordx4 v[90:91], v[68:71], off offset:512
	s_nop 1
	v_mov_b32_e32 v68, v112
	v_mov_b32_e32 v69, v113
	v_mov_b32_e32 v70, v114
	v_mov_b32_e32 v71, v115
	v_pk_add_f32 v[66:67], v[66:67], v[70:71]
	v_pk_add_f32 v[64:65], v[64:65], v[68:69]
	global_store_dwordx4 v[90:91], v[64:67], off offset:576

;     __device__ __forceinline__ bool next(int i, Unit& u) const { if (i != 0 || c >= n) return false; u.pm = 0; u.pn = c; u.kt0 = 0; u.nkt = ntk; u.piece = -1; return true; }
; #define PG8_STAGE(bufoff, gbase, voff) do { _Pragma("unroll") for (int _i = 0; _i < 2; ++_i) \
;         __builtin_amdgcn_global_load_lds((const unsigned*)((const char*)(gbase) + (voff)[_i]), (LAS unsigned*)(lds + (bufoff) + ldsw + _i * 8192), 16, 0, 0); } while (0)
; #define PG8_LDA(dst, b, h) do { _Pragma("unroll") for (int m = 0; m < 4; ++m) _Pragma("unroll") for (int k = 0; k < 2; ++k) dst[m][k] = *(const LAS bf16x8*)(lds + PG8_SA(b, h) + aoff + m * 2048 + k * 1024); } while (0)
; #define PG8_LDB(dst, b, h) do { _Pragma("unroll") for (int n = 0; n < 2; ++n) _Pragma("unroll") for (int k = 0; k < 2; ++k) dst[n][k] = *(const LAS bf16x8*)(lds + PG8_SB(b, h) + boff + n * 2048 + k * 1024); } while (0)
; template <class Epi, class Sched>
; __device__ __forceinline__ void gemm_phase(LAS unsigned char* lds, const Gemm g, const Sched& S, const Epi& E) {
;     ...
;     for (;;) {
;         const bool has_next = S.next(ui + 1, nxt);
;         const char* nA = has_next ? (const char*)g.A + (size_t)nxt.pm * tstepA + (size_t)nxt.pn * g.a_pn_off + (size_t)nxt.kt0 * kstep : cA; const char* nB = has_next ? (const char*)g.Bt + (size_t)nxt.pn * tstepB + (size_t)nxt.kt0 * kstep : cB;
;         const int nt = cur.nkt;
; #pragma unroll 1
;         for (int t = 0; t < nt; t += 2) {
;             const bool last = (t == nt - 2);
;             const char* a1 = cA + (size_t)(t + 1) * kstep;
;             const char* a2 = last ? nA : cA + (size_t)(t + 2) * kstep; const char* b2 = last ? nB : cB + (size_t)(t + 2) * kstep;
;             const char* a3 = a2 + kstep; const char* b3 = b2 + kstep;
;             PG8_LDB(B0, 0, 0); PG8_SCHED; PG8_LDA(At, 0, 0); PG8_STAGE(PG8_SA(1, 1), a1 + hstepA, voffA);
;             PG8_WAIT_L(8); PG8_BAR; PG8_WAIT_L(0); PG8_MMA(0, 0, At, B0); PG8_BAR; PG8_SCHED;
;             PG8_LDB(B1, 0, 1); PG8_STAGE(PG8_SB(0, 0), b2, voffB);
;     ...
; #pragma unroll
;         for (int a = 0; a < 2; ++a)
; #pragma unroll
;             for (int b = 0; b < 2; ++b)
; #pragma unroll
;                 for (int m = 0; m < 4; ++m)
; #pragma unroll
;                     for (int n = 0; n < 2; ++n) acc[a][b][m][n] = (f32x4){0.f, 0.f, 0.f, 0.f};
;         cur = nxt; cA = nA; cB = nB; ++ui;
.LBB0_1173:
	v_cmp_lt_i64_e32 vcc, s[34:35], v[138:139]
	s_lshl_b64 s[34:35], s[26:27], 17
	s_add_u32 s34, s59, s34
	s_addc_u32 s35, s60, s35
	s_and_b64 s[42:43], vcc, exec
	v_mov_b32_e32 v0, 0
	s_cselect_b32 s9, s35, s39
	s_cselect_b32 s27, s34, s38
	s_mov_b32 s29, 0
	s_mov_b64 s[42:43], -1
	s_mov_b64 s[44:45], 0
	v_mov_b32_e32 v1, v0
	v_mov_b32_e32 v2, v0
	v_mov_b32_e32 v3, v0
	v_mov_b32_e32 v4, v0
	v_mov_b32_e32 v5, v0
	v_mov_b32_e32 v6, v0
	v_mov_b32_e32 v7, v0
	v_mov_b32_e32 v16, v0
	v_mov_b32_e32 v17, v0
	v_mov_b32_e32 v18, v0
	v_mov_b32_e32 v19, v0
	v_mov_b32_e32 v20, v0
	v_mov_b32_e32 v21, v0
	v_mov_b32_e32 v22, v0
	v_mov_b32_e32 v23, v0
	v_mov_b32_e32 v32, v0
	v_mov_b32_e32 v33, v0
	v_mov_b32_e32 v34, v0
	v_mov_b32_e32 v35, v0
	v_mov_b32_e32 v36, v0
	v_mov_b32_e32 v37, v0
	v_mov_b32_e32 v38, v0
	v_mov_b32_e32 v39, v0
	v_mov_b32_e32 v48, v0
	v_mov_b32_e32 v49, v0
	v_mov_b32_e32 v50, v0
	v_mov_b32_e32 v51, v0
	v_mov_b32_e32 v52, v0
	v_mov_b32_e32 v53, v0
	v_mov_b32_e32 v54, v0
	v_mov_b32_e32 v55, v0
	v_mov_b32_e32 v8, v0
	v_mov_b32_e32 v9, v0
	v_mov_b32_e32 v10, v0
	v_mov_b32_e32 v11, v0
	v_mov_b32_e32 v12, v0
	v_mov_b32_e32 v13, v0
	v_mov_b32_e32 v14, v0
	v_mov_b32_e32 v15, v0
	v_mov_b32_e32 v24, v0
	v_mov_b32_e32 v25, v0
	v_mov_b32_e32 v26, v0
	v_mov_b32_e32 v27, v0
	v_mov_b32_e32 v28, v0
	v_mov_b32_e32 v29, v0
	v_mov_b32_e32 v30, v0
	v_mov_b32_e32 v31, v0
	v_mov_b32_e32 v40, v0
	v_mov_b32_e32 v41, v0
	v_mov_b32_e32 v42, v0
	v_mov_b32_e32 v43, v0
	v_mov_b32_e32 v44, v0
	v_mov_b32_e32 v45, v0
	v_mov_b32_e32 v46, v0
	v_mov_b32_e32 v47, v0
	v_mov_b32_e32 v56, v0
	v_mov_b32_e32 v57, v0
	v_mov_b32_e32 v58, v0
	v_mov_b32_e32 v59, v0
	v_mov_b32_e32 v60, v0
	v_mov_b32_e32 v61, v0
	v_mov_b32_e32 v62, v0
	v_mov_b32_e32 v63, v0
	v_mov_b32_e32 v64, v0
	v_mov_b32_e32 v65, v0
	v_mov_b32_e32 v66, v0
	v_mov_b32_e32 v67, v0
	v_mov_b32_e32 v68, v0
	v_mov_b32_e32 v69, v0
	v_mov_b32_e32 v70, v0
	v_mov_b32_e32 v71, v0
	v_mov_b32_e32 v80, v0
	v_mov_b32_e32 v81, v0
	v_mov_b32_e32 v82, v0
	v_mov_b32_e32 v83, v0
	v_mov_b32_e32 v84, v0
	v_mov_b32_e32 v85, v0
	v_mov_b32_e32 v86, v0
	v_mov_b32_e32 v87, v0
	v_mov_b32_e32 v96, v0
	v_mov_b32_e32 v97, v0
	v_mov_b32_e32 v98, v0
	v_mov_b32_e32 v99, v0
	v_mov_b32_e32 v100, v0
	v_mov_b32_e32 v101, v0
	v_mov_b32_e32 v102, v0
	v_mov_b32_e32 v103, v0
	v_mov_b32_e32 v112, v0
	v_mov_b32_e32 v113, v0
	v_mov_b32_e32 v114, v0
	v_mov_b32_e32 v115, v0
	v_mov_b32_e32 v116, v0
	v_mov_b32_e32 v117, v0
	v_mov_b32_e32 v118, v0
	v_mov_b32_e32 v119, v0
	v_mov_b32_e32 v72, v0
	v_mov_b32_e32 v73, v0
	v_mov_b32_e32 v74, v0
	v_mov_b32_e32 v75, v0
	v_mov_b32_e32 v76, v0
	v_mov_b32_e32 v77, v0
	v_mov_b32_e32 v78, v0
	v_mov_b32_e32 v79, v0
	v_mov_b32_e32 v88, v0
	v_mov_b32_e32 v89, v0
	v_mov_b32_e32 v90, v0
	v_mov_b32_e32 v91, v0
	v_mov_b32_e32 v92, v0
	v_mov_b32_e32 v93, v0
	v_mov_b32_e32 v94, v0
	v_mov_b32_e32 v95, v0
	v_mov_b32_e32 v104, v0
	v_mov_b32_e32 v105, v0
	v_mov_b32_e32 v106, v0
	v_mov_b32_e32 v107, v0
	v_mov_b32_e32 v108, v0
	v_mov_b32_e32 v109, v0
	v_mov_b32_e32 v110, v0
	v_mov_b32_e32 v111, v0
	v_mov_b32_e32 v120, v0
	v_mov_b32_e32 v121, v0
	v_mov_b32_e32 v122, v0
	v_mov_b32_e32 v123, v0
	v_mov_b32_e32 v124, v0
	v_mov_b32_e32 v125, v0
	v_mov_b32_e32 v126, v0
	v_mov_b32_e32 v127, v0
	s_lshr_b32 s88, s3, 8
	s_cmp_lg_u32 s88, 0
	s_cbranch_scc0 .Lprio_1174
	s_setprio 1
.Lprio_1174:
.LBB0_1174:
	s_add_u32 s48, s40, s29
	s_addc_u32 s49, s41, 0
	s_add_u32 s50, s48, 0x100
	s_addc_u32 s51, s49, 0
	s_and_b64 s[46:47], s[44:45], exec
	s_cselect_b32 s51, s31, s51
	s_cselect_b32 s50, s30, s50
	s_add_u32 s29, s38, s29
	s_addc_u32 s46, s39, 0
	s_add_u32 s29, s29, 0x100
	s_addc_u32 s46, s46, 0
	s_and_b64 s[44:45], s[44:45], exec
	s_cselect_b32 s53, s9, s46
	s_cselect_b32 s52, s27, s29
	s_add_u32 s54, s48, 0x40080
	s_addc_u32 s55, s49, 0
	s_add_i32 s80, s69, s56
	s_add_i32 m0, s37, 0xc000
	s_add_i32 s79, s37, 0xe000
	s_add_i32 s78, s80, 0x2000
	s_add_u32 s48, s52, 0x10000
	s_addc_u32 s49, s53, 0
	s_add_i32 s75, s70, s56
	ds_read_b128 v[142:145], v154
	ds_read_b128 v[146:149], v154 offset:1024
	ds_read_b128 v[162:165], v154 offset:2048
	ds_read_b128 v[168:171], v154 offset:3072
	s_add_i32 s74, s75, 0x2000
	s_add_i32 s73, 0, 0x18000
	s_add_u32 s46, s50, 0x40000
	s_addc_u32 s47, s51, 0
	s_add_i32 s72, s73, s56
	s_add_i32 s71, 0, 0x1c000
	s_add_i32 s29, s72, 0x2000
	s_add_u32 s44, s52, 0x10080
	s_addc_u32 s45, s53, 0
	s_add_i32 s77, s71, s56
	s_add_i32 s76, s77, 0x2000
	v_lshl_add_u64 v[158:159], s[54:55], 0, v[130:131]
	ds_read_b128 v[172:175], v155
	ds_read_b128 v[176:179], v155 offset:1024
	ds_read_b128 v[180:183], v155 offset:2048
	ds_read_b128 v[186:189], v155 offset:3072
	ds_read_b128 v[190:193], v155 offset:4096
	ds_read_b128 v[194:197], v155 offset:5120
	ds_read_b128 v[198:201], v155 offset:6144
	ds_read_b128 v[202:205], v155 offset:7168
	global_load_lds_dwordx4 v[158:159], off
	v_lshl_add_u64 v[158:159], s[54:55], 0, v[134:135]
	s_mov_b32 m0, s79
	s_nop 0
	global_load_lds_dwordx4 v[158:159], off
	s_waitcnt lgkmcnt(8)
	s_barrier
	s_waitcnt lgkmcnt(0)
	s_waitcnt lgkmcnt(0)
	v_mfma_f32_16x16x32_bf16 v[124:127], v[142:145], v[172:175], v[124:127]
	v_mfma_f32_16x16x32_bf16 v[120:123], v[162:165], v[172:175], v[120:123]
	v_mfma_f32_16x16x32_bf16 v[108:111], v[142:145], v[180:183], v[108:111]
	v_mfma_f32_16x16x32_bf16 v[104:107], v[162:165], v[180:183], v[104:107]
	v_mfma_f32_16x16x32_bf16 v[92:95], v[142:145], v[190:193], v[92:95]
	v_mfma_f32_16x16x32_bf16 v[88:91], v[162:165], v[190:193], v[88:91]
	v_mfma_f32_16x16x32_bf16 v[76:79], v[142:145], v[198:201], v[76:79]
	v_mfma_f32_16x16x32_bf16 v[72:75], v[162:165], v[198:201], v[72:75]
	v_mfma_f32_16x16x32_bf16 v[124:127], v[146:149], v[176:179], v[124:127]
	v_mfma_f32_16x16x32_bf16 v[120:123], v[168:171], v[176:179], v[120:123]
	v_mfma_f32_16x16x32_bf16 v[108:111], v[146:149], v[186:189], v[108:111]
	v_mfma_f32_16x16x32_bf16 v[104:107], v[168:171], v[186:189], v[104:107]
	v_mfma_f32_16x16x32_bf16 v[92:95], v[146:149], v[194:197], v[92:95]
	v_mfma_f32_16x16x32_bf16 v[88:91], v[168:171], v[194:197], v[88:91]
	v_mfma_f32_16x16x32_bf16 v[76:79], v[146:149], v[202:205], v[76:79]
	v_mfma_f32_16x16x32_bf16 v[72:75], v[168:171], v[202:205], v[72:75]
	s_barrier
; #define PG8_STAGE(bufoff, gbase, voff) do { _Pragma("unroll") for (int _i = 0; _i < 2; ++_i) \
;         __builtin_amdgcn_global_load_lds((const unsigned*)((const char*)(gbase) + (voff)[_i]), (LAS unsigned*)(lds + (bufoff) + ldsw + _i * 8192), 16, 0, 0); } while (0)
; #define PG8_LDA(dst, b, h) do { _Pragma("unroll") for (int m = 0; m < 4; ++m) _Pragma("unroll") for (int k = 0; k < 2; ++k) dst[m][k] = *(const LAS bf16x8*)(lds + PG8_SA(b, h) + aoff + m * 2048 + k * 1024); } while (0)
; #define PG8_LDB(dst, b, h) do { _Pragma("unroll") for (int n = 0; n < 2; ++n) _Pragma("unroll") for (int k = 0; k < 2; ++k) dst[n][k] = *(const LAS bf16x8*)(lds + PG8_SB(b, h) + boff + n * 2048 + k * 1024); } while (0)
; #define PG8_MMA(ai, bj, At, Bt) do { __builtin_amdgcn_s_setprio(1); _Pragma("unroll") for (int m = 0; m < 4; ++m) _Pragma("unroll") for (int n = 0; n < 2; ++n) _Pragma("unroll") for (int k = 0; k < 2; ++k) \
;         acc[ai][bj][m][n] = __builtin_amdgcn_mfma_f32_16x16x32_bf16(Bt[n][k], At[m][k], acc[ai][bj][m][n], 0, 0, 0); __builtin_amdgcn_s_setprio(0); } while (0)
; #define PG8_BAR __builtin_amdgcn_s_barrier()
; template <class Epi, class Sched>
; __device__ __forceinline__ void gemm_phase(LAS unsigned char* lds, const Gemm g, const Sched& S, const Epi& E) {
;     ...
;             PG8_LDB(B0, 0, 0); PG8_SCHED; PG8_LDA(At, 0, 0); PG8_STAGE(PG8_SA(1, 1), a1 + hstepA, voffA);
;             PG8_WAIT_L(8); PG8_BAR; PG8_WAIT_L(0); PG8_MMA(0, 0, At, B0); PG8_BAR; PG8_SCHED;
;             PG8_LDB(B1, 0, 1); PG8_STAGE(PG8_SB(0, 0), b2, voffB);
;             PG8_BAR; PG8_WAIT_L(0); if constexpr (!Epi::DIAG) PG8_MMA(0, 1, At, B1); PG8_BAR;
;             PG8_LDA(At, 0, 1); PG8_STAGE(PG8_SA(0, 0), a2, voffA);
;             PG8_BAR; PG8_WAIT_L(0); if constexpr (!Epi::DIAG) PG8_MMA(1, 0, At, B0); PG8_BAR; PG8_SCHED;
;             PG8_STAGE(PG8_SB(0, 1), b2 + hstepB, voffB);
;             PG8_WAIT_V(6); PG8_BAR; PG8_MMA(1, 1, At, B1); PG8_BAR;
;             PG8_LDB(B0, 1, 0); PG8_SCHED; PG8_LDA(At, 1, 0); PG8_STAGE(PG8_SA(0, 1), a2 + hstepA, voffA);
;             PG8_WAIT_L(8); PG8_BAR; PG8_WAIT_L(0); PG8_MMA(0, 0, At, B0); PG8_BAR; PG8_SCHED;
;             PG8_LDB(B1, 1, 1); PG8_STAGE(PG8_SB(1, 0), b3, voffB);
;             PG8_BAR; PG8_WAIT_L(0); if constexpr (!Epi::DIAG) PG8_MMA(0, 1, At, B1); PG8_BAR;
;             PG8_LDA(At, 1, 1); PG8_STAGE(PG8_SA(1, 0), a3, voffA);
	s_mov_b32 m0, s80
	v_lshl_add_u64 v[158:159], s[52:53], 0, v[132:133]
	ds_read_b128 v[206:209], v156
	ds_read_b128 v[210:213], v156 offset:1024
	ds_read_b128 v[214:217], v156 offset:2048
	ds_read_b128 v[218:221], v156 offset:3072
	global_load_lds_dwordx4 v[158:159], off
	v_lshl_add_u64 v[222:223], s[52:53], 0, v[136:137]
	s_mov_b32 m0, s78
	s_nop 0
	global_load_lds_dwordx4 v[222:223], off
	s_barrier
	s_waitcnt lgkmcnt(0)
	s_waitcnt lgkmcnt(0)
	v_mfma_f32_16x16x32_bf16 v[116:119], v[206:209], v[172:175], v[116:119]
	v_mfma_f32_16x16x32_bf16 v[112:115], v[214:217], v[172:175], v[112:115]
	v_mfma_f32_16x16x32_bf16 v[100:103], v[206:209], v[180:183], v[100:103]
	v_mfma_f32_16x16x32_bf16 v[96:99], v[214:217], v[180:183], v[96:99]
	v_mfma_f32_16x16x32_bf16 v[84:87], v[206:209], v[190:193], v[84:87]
	v_mfma_f32_16x16x32_bf16 v[80:83], v[214:217], v[190:193], v[80:83]
	v_mfma_f32_16x16x32_bf16 v[68:71], v[206:209], v[198:201], v[68:71]
	v_mfma_f32_16x16x32_bf16 v[64:67], v[214:217], v[198:201], v[64:67]
	v_mfma_f32_16x16x32_bf16 v[116:119], v[210:213], v[176:179], v[116:119]
	v_mfma_f32_16x16x32_bf16 v[112:115], v[218:221], v[176:179], v[112:115]
	v_mfma_f32_16x16x32_bf16 v[100:103], v[210:213], v[186:189], v[100:103]
	v_mfma_f32_16x16x32_bf16 v[96:99], v[218:221], v[186:189], v[96:99]
	v_mfma_f32_16x16x32_bf16 v[84:87], v[210:213], v[194:197], v[84:87]
	v_mfma_f32_16x16x32_bf16 v[80:83], v[218:221], v[194:197], v[80:83]
	v_mfma_f32_16x16x32_bf16 v[68:71], v[210:213], v[202:205], v[68:71]
	v_mfma_f32_16x16x32_bf16 v[64:67], v[218:221], v[202:205], v[64:67]
	s_mov_b32 m0, s37
	v_lshl_add_u64 v[224:225], s[50:51], 0, v[130:131]
	s_barrier
	ds_read_b128 v[172:175], v155 offset:16384
	ds_read_b128 v[176:179], v155 offset:17408
	ds_read_b128 v[180:183], v155 offset:18432
	ds_read_b128 v[186:189], v155 offset:19456
	ds_read_b128 v[190:193], v155 offset:20480
	ds_read_b128 v[194:197], v155 offset:21504
	ds_read_b128 v[198:201], v155 offset:22528
	ds_read_b128 v[202:205], v155 offset:23552
	global_load_lds_dwordx4 v[224:225], off
	v_lshl_add_u64 v[226:227], s[50:51], 0, v[134:135]
	s_mov_b32 m0, s61
	s_nop 0
	global_load_lds_dwordx4 v[226:227], off
	s_barrier
	s_waitcnt lgkmcnt(0)
	s_waitcnt lgkmcnt(0)
	v_mfma_f32_16x16x32_bf16 v[60:63], v[142:145], v[172:175], v[60:63]
	v_mfma_f32_16x16x32_bf16 v[56:59], v[162:165], v[172:175], v[56:59]
	v_mfma_f32_16x16x32_bf16 v[44:47], v[142:145], v[180:183], v[44:47]
	v_mfma_f32_16x16x32_bf16 v[40:43], v[162:165], v[180:183], v[40:43]
	v_mfma_f32_16x16x32_bf16 v[28:31], v[142:145], v[190:193], v[28:31]
	v_mfma_f32_16x16x32_bf16 v[24:27], v[162:165], v[190:193], v[24:27]
	v_mfma_f32_16x16x32_bf16 v[12:15], v[142:145], v[198:201], v[12:15]
	v_mfma_f32_16x16x32_bf16 v[8:11], v[162:165], v[198:201], v[8:11]
	v_mfma_f32_16x16x32_bf16 v[60:63], v[146:149], v[176:179], v[60:63]
	v_mfma_f32_16x16x32_bf16 v[56:59], v[168:171], v[176:179], v[56:59]
	v_mfma_f32_16x16x32_bf16 v[44:47], v[146:149], v[186:189], v[44:47]
	v_mfma_f32_16x16x32_bf16 v[40:43], v[168:171], v[186:189], v[40:43]
	v_mfma_f32_16x16x32_bf16 v[28:31], v[146:149], v[194:197], v[28:31]
	v_mfma_f32_16x16x32_bf16 v[24:27], v[168:171], v[194:197], v[24:27]
	v_mfma_f32_16x16x32_bf16 v[12:15], v[146:149], v[202:205], v[12:15]
	v_mfma_f32_16x16x32_bf16 v[8:11], v[168:171], v[202:205], v[8:11]
	s_barrier
	s_mov_b32 m0, s75
	v_lshl_add_u64 v[142:143], s[48:49], 0, v[132:133]
	global_load_lds_dwordx4 v[142:143], off
	v_lshl_add_u64 v[142:143], s[48:49], 0, v[136:137]
	s_mov_b32 m0, s74
	s_nop 0
	global_load_lds_dwordx4 v[142:143], off
	s_waitcnt vmcnt(6)
	s_barrier
	v_mfma_f32_16x16x32_bf16 v[52:55], v[206:209], v[172:175], v[52:55]
	v_mfma_f32_16x16x32_bf16 v[48:51], v[214:217], v[172:175], v[48:51]
	v_mfma_f32_16x16x32_bf16 v[36:39], v[206:209], v[180:183], v[36:39]
	v_mfma_f32_16x16x32_bf16 v[32:35], v[214:217], v[180:183], v[32:35]
	v_mfma_f32_16x16x32_bf16 v[20:23], v[206:209], v[190:193], v[20:23]
	v_mfma_f32_16x16x32_bf16 v[16:19], v[214:217], v[190:193], v[16:19]
	v_mfma_f32_16x16x32_bf16 v[4:7], v[206:209], v[198:201], v[4:7]
	v_mfma_f32_16x16x32_bf16 v[0:3], v[214:217], v[198:201], v[0:3]
	v_mfma_f32_16x16x32_bf16 v[52:55], v[210:213], v[176:179], v[52:55]
	v_mfma_f32_16x16x32_bf16 v[48:51], v[218:221], v[176:179], v[48:51]
	v_mfma_f32_16x16x32_bf16 v[36:39], v[210:213], v[186:189], v[36:39]
	v_mfma_f32_16x16x32_bf16 v[32:35], v[218:221], v[186:189], v[32:35]
	v_mfma_f32_16x16x32_bf16 v[20:23], v[210:213], v[194:197], v[20:23]
	v_mfma_f32_16x16x32_bf16 v[16:19], v[218:221], v[194:197], v[16:19]
	v_mfma_f32_16x16x32_bf16 v[4:7], v[210:213], v[202:205], v[4:7]
	v_mfma_f32_16x16x32_bf16 v[0:3], v[218:221], v[202:205], v[0:3]
	v_add_u32_e32 v157, s73, v152
	s_barrier
	ds_read_b128 v[142:145], v157
	ds_read_b128 v[146:149], v157 offset:1024
	ds_read_b128 v[162:165], v157 offset:2048
	ds_read_b128 v[168:171], v157 offset:3072
	s_mov_b32 m0, s62
	v_lshl_add_u64 v[206:207], s[46:47], 0, v[130:131]
	ds_read_b128 v[172:175], v155 offset:32768
	ds_read_b128 v[176:179], v155 offset:33792
	ds_read_b128 v[180:183], v155 offset:34816
	ds_read_b128 v[186:189], v155 offset:35840
	ds_read_b128 v[190:193], v155 offset:36864
	ds_read_b128 v[194:197], v155 offset:37888
	ds_read_b128 v[198:201], v155 offset:38912
	ds_read_b128 v[202:205], v155 offset:39936
	global_load_lds_dwordx4 v[206:207], off
	v_lshl_add_u64 v[206:207], s[46:47], 0, v[134:135]
	s_mov_b32 m0, s63
	s_nop 0
	global_load_lds_dwordx4 v[206:207], off
	s_waitcnt lgkmcnt(8)
	s_barrier
; __device__ __forceinline__ unsigned pk2(float lo, float hi) { const f32x2 v = {lo, hi}; const bf16x2_hw b = __builtin_convertvector(v, bf16x2_hw); return __builtin_bit_cast(unsigned, b); }
; #define PG8_STAGE(bufoff, gbase, voff) do { _Pragma("unroll") for (int _i = 0; _i < 2; ++_i) \
;         __builtin_amdgcn_global_load_lds((const unsigned*)((const char*)(gbase) + (voff)[_i]), (LAS unsigned*)(lds + (bufoff) + ldsw + _i * 8192), 16, 0, 0); } while (0)
; #define PG8_LDA(dst, b, h) do { _Pragma("unroll") for (int m = 0; m < 4; ++m) _Pragma("unroll") for (int k = 0; k < 2; ++k) dst[m][k] = *(const LAS bf16x8*)(lds + PG8_SA(b, h) + aoff + m * 2048 + k * 1024); } while (0)
; #define PG8_WAIT_V(n) asm volatile("s_waitcnt vmcnt(" #n ")" ::: "memory")
; #define PG8_WAIT_L(n) asm volatile("s_waitcnt lgkmcnt(" #n ")" ::: "memory")
; #define PG8_BAR __builtin_amdgcn_s_barrier()
; #define PG8_SCHED __builtin_amdgcn_sched_barrier(0)
; template <class Epi, class Sched>
; __device__ __forceinline__ void gemm_phase(LAS unsigned char* lds, const Gemm g, const Sched& S, const Epi& E) {
;     ...
;             PG8_LDA(At, 1, 1); PG8_STAGE(PG8_SA(1, 0), a3, voffA);
;             PG8_BAR; PG8_WAIT_L(0); if constexpr (!Epi::DIAG) PG8_MMA(1, 0, At, B0); PG8_BAR; PG8_SCHED;
;             PG8_STAGE(PG8_SB(1, 1), b3 + hstepB, voffB);
;             PG8_WAIT_V(6); PG8_BAR; PG8_MMA(1, 1, At, B1); PG8_BAR;
;         }
;         E(acc, cur, wr, wc, fr, fq);
;     __device__ __forceinline__ void operator()(const Acc& acc, const Unit& u, int wr, int wc, int fr, int fq) const {
;         const int row0 = u.pm * BM + wr * 64 + fr, col0 = u.pn * BM + wc * 32 + 8 * fq;
; #pragma unroll
;         for (int ai = 0; ai < 2; ++ai)
; #pragma unroll
;             for (int m = 0; m < 4; ++m) { bf16_t* rowp = O + (size_t)(row0 + ai * HALF + m * 16) * ldc + col_off + col0;
; #pragma unroll
;                 for (int bj = 0; bj < 2; ++bj) { f32x4 v0 = acc[ai][bj][m][0], v1 = acc[ai][bj][m][1];
;                     if (scale) { v0 *= *(const f32x4*)(scale + col0 + bj * HALF); v1 *= *(const f32x4*)(scale + col0 + bj * HALF + 4); }
;                     u32x4 w; w.x = pk2(v0[0], v0[1]); w.y = pk2(v0[2], v0[3]); w.z = pk2(v1[0], v1[1]); w.w = pk2(v1[2], v1[3]);
;                     *(u32x4*)(rowp + bj * HALF) = w; }
	s_waitcnt lgkmcnt(0)
	s_waitcnt lgkmcnt(0)
	v_mfma_f32_16x16x32_bf16 v[124:127], v[142:145], v[172:175], v[124:127]
	v_mfma_f32_16x16x32_bf16 v[120:123], v[162:165], v[172:175], v[120:123]
	v_mfma_f32_16x16x32_bf16 v[108:111], v[142:145], v[180:183], v[108:111]
	v_mfma_f32_16x16x32_bf16 v[104:107], v[162:165], v[180:183], v[104:107]
	v_mfma_f32_16x16x32_bf16 v[92:95], v[142:145], v[190:193], v[92:95]
	v_mfma_f32_16x16x32_bf16 v[88:91], v[162:165], v[190:193], v[88:91]
	v_mfma_f32_16x16x32_bf16 v[76:79], v[142:145], v[198:201], v[76:79]
	v_mfma_f32_16x16x32_bf16 v[72:75], v[162:165], v[198:201], v[72:75]
	v_mfma_f32_16x16x32_bf16 v[124:127], v[146:149], v[176:179], v[124:127]
	v_mfma_f32_16x16x32_bf16 v[120:123], v[168:171], v[176:179], v[120:123]
	v_mfma_f32_16x16x32_bf16 v[108:111], v[146:149], v[186:189], v[108:111]
	v_mfma_f32_16x16x32_bf16 v[104:107], v[168:171], v[186:189], v[104:107]
	v_mfma_f32_16x16x32_bf16 v[92:95], v[146:149], v[194:197], v[92:95]
	v_mfma_f32_16x16x32_bf16 v[88:91], v[168:171], v[194:197], v[88:91]
	v_mfma_f32_16x16x32_bf16 v[76:79], v[146:149], v[202:205], v[76:79]
	v_mfma_f32_16x16x32_bf16 v[72:75], v[168:171], v[202:205], v[72:75]
	s_barrier
	s_mov_b32 m0, s72
	v_add_u32_e32 v157, s71, v152
	v_lshl_add_u64 v[158:159], v[158:159], 0, s[16:17]
	ds_read_b128 v[206:209], v157
	ds_read_b128 v[210:213], v157 offset:1024
	ds_read_b128 v[214:217], v157 offset:2048
	ds_read_b128 v[218:221], v157 offset:3072
	global_load_lds_dwordx4 v[158:159], off
	v_lshl_add_u64 v[158:159], v[222:223], 0, s[16:17]
	s_mov_b32 m0, s29
	s_nop 0
	global_load_lds_dwordx4 v[158:159], off
	s_barrier
	s_waitcnt lgkmcnt(0)
	s_waitcnt lgkmcnt(0)
	v_mfma_f32_16x16x32_bf16 v[116:119], v[206:209], v[172:175], v[116:119]
	v_mfma_f32_16x16x32_bf16 v[112:115], v[214:217], v[172:175], v[112:115]
	v_mfma_f32_16x16x32_bf16 v[100:103], v[206:209], v[180:183], v[100:103]
	v_mfma_f32_16x16x32_bf16 v[96:99], v[214:217], v[180:183], v[96:99]
	v_mfma_f32_16x16x32_bf16 v[84:87], v[206:209], v[190:193], v[84:87]
	v_mfma_f32_16x16x32_bf16 v[80:83], v[214:217], v[190:193], v[80:83]
	v_mfma_f32_16x16x32_bf16 v[68:71], v[206:209], v[198:201], v[68:71]
	v_mfma_f32_16x16x32_bf16 v[64:67], v[214:217], v[198:201], v[64:67]
	v_mfma_f32_16x16x32_bf16 v[116:119], v[210:213], v[176:179], v[116:119]
	v_mfma_f32_16x16x32_bf16 v[112:115], v[218:221], v[176:179], v[112:115]
	v_mfma_f32_16x16x32_bf16 v[100:103], v[210:213], v[186:189], v[100:103]
	v_mfma_f32_16x16x32_bf16 v[96:99], v[218:221], v[186:189], v[96:99]
	v_mfma_f32_16x16x32_bf16 v[84:87], v[210:213], v[194:197], v[84:87]
	v_mfma_f32_16x16x32_bf16 v[80:83], v[218:221], v[194:197], v[80:83]
	v_mfma_f32_16x16x32_bf16 v[68:71], v[210:213], v[202:205], v[68:71]
	v_mfma_f32_16x16x32_bf16 v[64:67], v[218:221], v[202:205], v[64:67]
	s_mov_b32 m0, s67
	v_lshl_add_u64 v[158:159], v[224:225], 0, s[16:17]
	s_barrier
	ds_read_b128 v[172:175], v155 offset:49152
	ds_read_b128 v[176:179], v155 offset:50176
	ds_read_b128 v[180:183], v155 offset:51200
	ds_read_b128 v[186:189], v155 offset:52224
	ds_read_b128 v[190:193], v155 offset:53248
	ds_read_b128 v[194:197], v155 offset:54272
	ds_read_b128 v[198:201], v155 offset:55296
	ds_read_b128 v[202:205], v155 offset:56320
	global_load_lds_dwordx4 v[158:159], off
	v_lshl_add_u64 v[158:159], v[226:227], 0, s[16:17]
	s_mov_b32 m0, s68
	s_nop 0
	global_load_lds_dwordx4 v[158:159], off
	s_barrier
	s_waitcnt lgkmcnt(0)
	s_waitcnt lgkmcnt(0)
	v_mfma_f32_16x16x32_bf16 v[60:63], v[142:145], v[172:175], v[60:63]
	v_mfma_f32_16x16x32_bf16 v[56:59], v[162:165], v[172:175], v[56:59]
	v_mfma_f32_16x16x32_bf16 v[44:47], v[142:145], v[180:183], v[44:47]
	v_mfma_f32_16x16x32_bf16 v[40:43], v[162:165], v[180:183], v[40:43]
	v_mfma_f32_16x16x32_bf16 v[28:31], v[142:145], v[190:193], v[28:31]
	v_mfma_f32_16x16x32_bf16 v[24:27], v[162:165], v[190:193], v[24:27]
	v_mfma_f32_16x16x32_bf16 v[12:15], v[142:145], v[198:201], v[12:15]
	v_mfma_f32_16x16x32_bf16 v[8:11], v[162:165], v[198:201], v[8:11]
	v_mfma_f32_16x16x32_bf16 v[60:63], v[146:149], v[176:179], v[60:63]
	v_mfma_f32_16x16x32_bf16 v[56:59], v[168:171], v[176:179], v[56:59]
	v_mfma_f32_16x16x32_bf16 v[44:47], v[146:149], v[186:189], v[44:47]
	v_mfma_f32_16x16x32_bf16 v[40:43], v[168:171], v[186:189], v[40:43]
	v_mfma_f32_16x16x32_bf16 v[28:31], v[146:149], v[194:197], v[28:31]
	v_mfma_f32_16x16x32_bf16 v[24:27], v[168:171], v[194:197], v[24:27]
	v_mfma_f32_16x16x32_bf16 v[12:15], v[146:149], v[202:205], v[12:15]
	v_mfma_f32_16x16x32_bf16 v[8:11], v[168:171], v[202:205], v[8:11]
	s_barrier
	s_mov_b32 m0, s77
	v_lshl_add_u64 v[142:143], s[44:45], 0, v[132:133]
	global_load_lds_dwordx4 v[142:143], off
	v_lshl_add_u64 v[142:143], s[44:45], 0, v[136:137]
	s_mov_b32 m0, s76
	s_nop 0
	global_load_lds_dwordx4 v[142:143], off
	s_waitcnt vmcnt(6)
	s_barrier
	v_mfma_f32_16x16x32_bf16 v[52:55], v[206:209], v[172:175], v[52:55]
	v_mfma_f32_16x16x32_bf16 v[48:51], v[214:217], v[172:175], v[48:51]
	v_mfma_f32_16x16x32_bf16 v[36:39], v[206:209], v[180:183], v[36:39]
	v_mfma_f32_16x16x32_bf16 v[32:35], v[214:217], v[180:183], v[32:35]
	v_mfma_f32_16x16x32_bf16 v[20:23], v[206:209], v[190:193], v[20:23]
	v_mfma_f32_16x16x32_bf16 v[16:19], v[214:217], v[190:193], v[16:19]
	v_mfma_f32_16x16x32_bf16 v[4:7], v[206:209], v[198:201], v[4:7]
	v_mfma_f32_16x16x32_bf16 v[0:3], v[214:217], v[198:201], v[0:3]
	v_mfma_f32_16x16x32_bf16 v[52:55], v[210:213], v[176:179], v[52:55]
	v_mfma_f32_16x16x32_bf16 v[48:51], v[218:221], v[176:179], v[48:51]
	v_mfma_f32_16x16x32_bf16 v[36:39], v[210:213], v[186:189], v[36:39]
	v_mfma_f32_16x16x32_bf16 v[32:35], v[218:221], v[186:189], v[32:35]
	v_mfma_f32_16x16x32_bf16 v[20:23], v[210:213], v[194:197], v[20:23]
	v_mfma_f32_16x16x32_bf16 v[16:19], v[218:221], v[194:197], v[16:19]
	v_mfma_f32_16x16x32_bf16 v[4:7], v[210:213], v[202:205], v[4:7]
	v_mfma_f32_16x16x32_bf16 v[0:3], v[218:221], v[202:205], v[0:3]
	s_movk_i32 s29, 0x100
	s_andn2_b64 vcc, exec, s[42:43]
	s_mov_b64 s[44:45], -1
	s_mov_b64 s[42:43], 0
	s_barrier
	s_cbranch_vccz .LBB0_1174
	s_setprio 0
	v_lshl_or_b32 v144, s8, 8, v153
	v_ashrrev_i32_e32 v145, 31, v144
	v_cndmask_b32_e64 v142, 0, 1, s[14:15]
	v_cmp_ne_u32_e64 s[8:9], 1, v142
	s_andn2_b64 vcc, exec, s[14:15]
	v_lshl_add_u64 v[142:143], v[144:145], 2, s[10:11]
	s_cbranch_vccnz .LBB0_1177
	global_load_dwordx4 v[186:189], v[142:143], off
	global_load_dwordx4 v[190:193], v[142:143], off offset:16
	global_load_dwordx4 v[194:197], v[142:143], off offset:512
	global_load_dwordx4 v[198:201], v[142:143], off offset:528
	s_waitcnt vmcnt(0)
	s_nop 1
	v_mov_b32_e32 v146, v186
	v_mov_b32_e32 v147, v187
	v_mov_b32_e32 v148, v188
	v_mov_b32_e32 v149, v189
	s_nop 1
	v_mov_b32_e32 v162, v190
	v_mov_b32_e32 v163, v191
	v_mov_b32_e32 v164, v192
	v_mov_b32_e32 v165, v193
	v_pk_mul_f32 v[126:127], v[126:127], v[148:149]
	v_pk_mul_f32 v[124:125], v[124:125], v[146:147]
	v_pk_mul_f32 v[122:123], v[122:123], v[164:165]
	v_pk_mul_f32 v[120:121], v[120:121], v[162:163]
